# P5 start stagger: odd 8-CU groups wait 8us so the two halves' epilogue HBM bursts interleave
# baseline (speedup 1.0000x reference)
.LBB0_584:
	s_lshr_b32 s98, s70, 3
	s_and_b32 s98, s98, 1
	s_cmp_eq_u32 s98, 0
	s_cbranch_scc1 .Lstagp5_done
	s_mul_i32 s101, s98, 800
	s_memrealtime s[98:99]
	s_waitcnt lgkmcnt(0)
	s_add_u32 s101, s98, s101
.Lstagp5_wait:
	s_sleep 8
	s_memrealtime s[98:99]
	s_waitcnt lgkmcnt(0)
	s_sub_u32 s98, s98, s101
	s_cmp_lt_i32 s98, 0
	s_cbranch_scc1 .Lstagp5_wait
.Lstagp5_done:
	s_cmp_lt_i32 s30, 6
	s_cselect_b64 s[2:3], -1, 0
	s_add_u32 s8, s28, 0x10000
	s_addc_u32 s9, s29, 0
	s_add_u32 s4, s28, 0xd000000
	s_addc_u32 s5, s29, 0
	s_and_b64 s[10:11], s[2:3], s[0:1]
	s_andn2_b64 vcc, exec, s[10:11]
	s_cbranch_vccnz .LBB0_625
	s_cmpk_lt_i32 s70, 0x200
	s_cselect_b64 s[0:1], -1, 0
	s_cmpk_gt_i32 s70, 0x1ff
	v_readfirstlane_b32 s2, v189
	s_cbranch_scc1 .LBB0_587
	s_ashr_i32 s3, s70, 31
	s_lshr_b32 s3, s3, 29
	s_add_i32 s3, s70, s3
	s_and_b32 s12, s3, -8
	s_sub_i32 s12, s70, s12
	s_lshl_b32 s14, s12, 6
	s_ashr_i32 s3, s3, 3
	s_mul_i32 s13, s12, 0x41
	s_cmp_lt_i32 s12, 0
	s_cselect_b32 s12, s13, s14
	s_add_i32 s3, s12, s3
	s_ashr_i32 s12, s3, 31
	s_lshr_b32 s12, s12, 27
	s_add_i32 s12, s3, s12
	s_ashr_i32 s13, s12, 5
	s_andn2_b32 s12, s12, 31
	s_sub_i32 s3, s3, s12
	s_bfe_i32 s12, s3, 0x80000
	s_bfe_u32 s12, s12, 0x3000c
	s_add_i32 s12, s3, s12
	s_bfe_i32 s14, s12, 0x80000
	s_and_b32 s12, s12, 0xf8
	s_sub_i32 s3, s3, s12
	s_lshl_b32 s13, s13, 3
	s_sext_i32_i16 s14, s14
	s_sext_i32_i8 s3, s3
	s_add_i32 s44, s13, s3
	s_ashr_i32 s42, s14, 3
